# attention epilogue: 16 half-wave dwordx2 stores widened to 8 dwordx4 via v_permlane32_swap (on top of the PROMPT epilogue widening)
# speedup vs baseline: 1.0040x; 1.0040x over previous
.LBB0_333:
	v_mbcnt_lo_u32_b32 v240, -1, 0
	v_mbcnt_hi_u32_b32 v240, -1, v240
	v_and_b32_e32 v240, 32, v240
	v_lshrrev_b32_e32 v240, 2, v240
	v_mov_b32_e32 v241, 0
	ds_bpermute_b32 v64, v145, v148
	s_waitcnt vmcnt(0)
	v_mul_f32_e32 v65, 0x3fb8aa3b, v146
	v_exp_f32_e32 v67, v65
	s_add_u32 s0, s8, s6
	v_lshlrev_b32_e32 v160, 1, v147
	s_waitcnt lgkmcnt(0)
	v_add_f32_e32 v64, v148, v64
	v_add_f32_e32 v66, v67, v64
	v_div_scale_f32 v68, s[4:5], v66, v66, 1.0
	v_rcp_f32_e32 v69, v68
	s_addc_u32 s1, s9, s7
	v_lshl_add_u64 v[64:65], s[0:1], 0, v[160:161]
	v_fma_f32 v70, -v68, v69, 1.0
	v_fmac_f32_e32 v69, v70, v69
	v_div_scale_f32 v70, vcc, 1.0, v66, 1.0
	v_mul_f32_e32 v71, v70, v69
	v_fma_f32 v72, -v68, v71, v70
	v_fmac_f32_e32 v71, v72, v69
	v_fma_f32 v68, -v68, v71, v70
	v_div_fmas_f32 v68, v68, v69, v71
	v_div_fixup_f32 v66, v68, v66, 1.0
	v_lshlrev_b64 v[68:69], 11, v[142:143]
	v_pk_mul_f32 v[32:33], v[32:33], v[66:67] op_sel_hi:[1,0]
	v_pk_mul_f32 v[34:35], v[34:35], v[66:67] op_sel_hi:[1,0]
	v_lshl_add_u64 v[68:69], v[64:65], 0, v[68:69]
	v_lshl_add_u64 v[188:189], v[240:241], 0, v[68:69]
	v_cvt_pk_bf16_f32 v184, v32, v33
	v_cvt_pk_bf16_f32 v185, v34, v35
	v_pk_mul_f32 v[32:33], v[36:37], v[66:67] op_sel_hi:[1,0]
	v_pk_mul_f32 v[34:35], v[38:39], v[66:67] op_sel_hi:[1,0]
	ds_bpermute_b32 v36, v145, v132
	v_cvt_pk_bf16_f32 v186, v32, v33
	v_cvt_pk_bf16_f32 v187, v34, v35
	s_nop 1
	v_permlane32_swap_b32 v184, v186
	v_permlane32_swap_b32 v185, v187
	global_store_dwordx4 v[188:189], v[184:187], off offset:64
	v_pk_mul_f32 v[32:33], v[40:41], v[66:67] op_sel_hi:[1,0]
	v_pk_mul_f32 v[34:35], v[42:43], v[66:67] op_sel_hi:[1,0]
	v_cvt_pk_bf16_f32 v184, v32, v33
	v_cvt_pk_bf16_f32 v185, v34, v35
	v_pk_mul_f32 v[32:33], v[44:45], v[66:67] op_sel_hi:[1,0]
	v_pk_mul_f32 v[34:35], v[46:47], v[66:67] op_sel_hi:[1,0]
	v_cvt_pk_bf16_f32 v186, v32, v33
	s_waitcnt lgkmcnt(0)
	v_add_f32_e32 v33, v132, v36
	v_add_f32_e32 v36, v67, v33
	v_div_scale_f32 v37, s[0:1], v36, v36, 1.0
	v_rcp_f32_e32 v38, v37
	v_cvt_pk_bf16_f32 v187, v34, v35
	s_nop 1
	v_permlane32_swap_b32 v184, v186
	v_permlane32_swap_b32 v185, v187
	global_store_dwordx4 v[188:189], v[184:187], off offset:96
	v_pk_mul_f32 v[48:49], v[48:49], v[66:67] op_sel_hi:[1,0]
	v_fma_f32 v32, -v37, v38, 1.0
	v_fmac_f32_e32 v38, v32, v38
	v_div_scale_f32 v32, vcc, 1.0, v36, 1.0
	v_mul_f32_e32 v33, v32, v38
	v_fma_f32 v34, -v37, v33, v32
	v_fmac_f32_e32 v33, v34, v38
	v_fma_f32 v32, -v37, v33, v32
	v_div_fmas_f32 v32, v32, v38, v33
	v_div_fixup_f32 v32, v32, v36, 1.0
	v_lshlrev_b64 v[34:35], 11, v[140:141]
	v_pk_mul_f32 v[0:1], v[0:1], v[32:33] op_sel_hi:[1,0]
	v_pk_mul_f32 v[2:3], v[2:3], v[32:33] op_sel_hi:[1,0]
	v_lshl_add_u64 v[34:35], v[64:65], 0, v[34:35]
	v_lshl_add_u64 v[190:191], v[240:241], 0, v[34:35]
	v_cvt_pk_bf16_f32 v236, v0, v1
	v_cvt_pk_bf16_f32 v237, v2, v3
	v_pk_mul_f32 v[0:1], v[4:5], v[32:33] op_sel_hi:[1,0]
	v_pk_mul_f32 v[2:3], v[6:7], v[32:33] op_sel_hi:[1,0]
	v_cvt_pk_bf16_f32 v238, v0, v1
	v_cvt_pk_bf16_f32 v239, v2, v3
	s_nop 1
	v_permlane32_swap_b32 v236, v238
	v_permlane32_swap_b32 v237, v239
	global_store_dwordx4 v[190:191], v[236:239], off
	v_pk_mul_f32 v[0:1], v[8:9], v[32:33] op_sel_hi:[1,0]
	v_pk_mul_f32 v[2:3], v[10:11], v[32:33] op_sel_hi:[1,0]
	v_cvt_pk_bf16_f32 v236, v0, v1
	v_cvt_pk_bf16_f32 v237, v2, v3
	v_pk_mul_f32 v[0:1], v[12:13], v[32:33] op_sel_hi:[1,0]
	v_pk_mul_f32 v[2:3], v[14:15], v[32:33] op_sel_hi:[1,0]
	v_cvt_pk_bf16_f32 v238, v0, v1
	v_cvt_pk_bf16_f32 v239, v2, v3
	v_pk_mul_f32 v[50:51], v[50:51], v[66:67] op_sel_hi:[1,0]
	s_nop 1
	v_permlane32_swap_b32 v236, v238
	v_permlane32_swap_b32 v237, v239
	global_store_dwordx4 v[190:191], v[236:239], off offset:32
	v_pk_mul_f32 v[0:1], v[16:17], v[32:33] op_sel_hi:[1,0]
	v_pk_mul_f32 v[2:3], v[18:19], v[32:33] op_sel_hi:[1,0]
	v_cvt_pk_bf16_f32 v184, v48, v49
	v_cvt_pk_bf16_f32 v185, v50, v51
	v_cvt_pk_bf16_f32 v236, v0, v1
	v_cvt_pk_bf16_f32 v237, v2, v3
	v_pk_mul_f32 v[48:49], v[52:53], v[66:67] op_sel_hi:[1,0]
	v_pk_mul_f32 v[50:51], v[54:55], v[66:67] op_sel_hi:[1,0]
	v_pk_mul_f32 v[0:1], v[20:21], v[32:33] op_sel_hi:[1,0]
	v_pk_mul_f32 v[2:3], v[22:23], v[32:33] op_sel_hi:[1,0]
	v_cvt_pk_bf16_f32 v186, v48, v49
	v_cvt_pk_bf16_f32 v187, v50, v51
	v_cvt_pk_bf16_f32 v238, v0, v1
	v_cvt_pk_bf16_f32 v239, v2, v3
	s_nop 1
	v_permlane32_swap_b32 v184, v186
	v_permlane32_swap_b32 v185, v187
	global_store_dwordx4 v[188:189], v[184:187], off
	v_pk_mul_f32 v[48:49], v[56:57], v[66:67] op_sel_hi:[1,0]
	v_pk_mul_f32 v[50:51], v[58:59], v[66:67] op_sel_hi:[1,0]
	s_nop 1
	v_permlane32_swap_b32 v236, v238
	v_permlane32_swap_b32 v237, v239
	global_store_dwordx4 v[190:191], v[236:239], off offset:64
	v_pk_mul_f32 v[0:1], v[24:25], v[32:33] op_sel_hi:[1,0]
	v_pk_mul_f32 v[2:3], v[26:27], v[32:33] op_sel_hi:[1,0]
	v_cvt_pk_bf16_f32 v184, v48, v49
	v_cvt_pk_bf16_f32 v185, v50, v51
	v_cvt_pk_bf16_f32 v236, v0, v1
	v_cvt_pk_bf16_f32 v237, v2, v3
	v_pk_mul_f32 v[48:49], v[60:61], v[66:67] op_sel_hi:[1,0]
	v_pk_mul_f32 v[50:51], v[62:63], v[66:67] op_sel_hi:[1,0]
	v_pk_mul_f32 v[0:1], v[28:29], v[32:33] op_sel_hi:[1,0]
	v_pk_mul_f32 v[2:3], v[30:31], v[32:33] op_sel_hi:[1,0]
	v_cvt_pk_bf16_f32 v186, v48, v49
	v_cvt_pk_bf16_f32 v187, v50, v51
	v_cvt_pk_bf16_f32 v238, v0, v1
	v_cvt_pk_bf16_f32 v239, v2, v3
	s_nop 1
	v_permlane32_swap_b32 v184, v186
	v_permlane32_swap_b32 v185, v187
	global_store_dwordx4 v[188:189], v[184:187], off offset:32
	s_nop 1
	v_permlane32_swap_b32 v236, v238
	v_permlane32_swap_b32 v237, v239
	global_store_dwordx4 v[190:191], v[236:239], off offset:96
	s_barrier
